# mix1a: co-resident blocks take poolc tiles of complementary window classes (long-window gather traffic spread evenly over CUs) + kvstate tiles moved to the short-window blocks
# speedup vs baseline: 1.0040x; 1.0040x over previous
.LBB0_500:
	s_or_b64 exec, exec, s[0:1]
	s_cmpk_gt_i32 s2, 0x7ff
	s_waitcnt lgkmcnt(0)
	s_barrier
	s_cbranch_scc1 .LBB0_515
	v_xor_b32_e32 v1, v128, v131
	v_lshlrev_b32_e32 v1, 3, v1
	s_movk_i32 s1, 0x1e0
	v_and_b32_e32 v2, 56, v1
	v_and_b32_e32 v1, 0x60, v158
	v_and_or_b32 v4, v153, s1, v138
	v_bitop3_b32 v6, v128, v139, 3 bitop3:0x6c
	s_movk_i32 s0, 0x60
	v_lshlrev_b32_e32 v7, 4, v6
	v_lshlrev_b32_e32 v9, 7, v4
	v_lshlrev_b32_e32 v4, 7, v1
	v_and_b32_e32 v6, 0x1f0, v153
	s_movk_i32 s1, 0x50
	v_bitop3_b32 v24, v4, v6, s0 bitop3:0xf6
	s_movk_i32 s0, 0x70
	v_or_b32_e32 v13, v4, v6
	v_bitop3_b32 v15, v4, v6, 16 bitop3:0xf6
	v_bitop3_b32 v17, v4, v6, 32 bitop3:0xf6
	v_bitop3_b32 v19, v4, v6, 48 bitop3:0xf6
	v_bitop3_b32 v22, v4, v6, 64 bitop3:0xf6
	v_bitop3_b32 v23, v4, v6, s1 bitop3:0xf6
	v_bitop3_b32 v25, v4, v6, s0 bitop3:0xf6
	v_lshlrev_b32_e32 v10, 13, v135
	v_lshl_add_u32 v4, v134, 3, v138
	v_lshlrev_b32_e32 v8, 5, v138
	v_or3_b32 v67, v10, v137, v8
	v_add_u32_e32 v8, 0x60, v4
	v_lshl_or_b32 v6, v134, 11, v10
	v_and_b32_e32 v8, 0x7f, v8
	v_lshl_or_b32 v148, v4, 2, v6
	v_lshl_or_b32 v149, v8, 2, v6
	v_add_u32_e32 v4, 0x70, v4
	v_add_u32_e32 v8, 8, v133
	v_lshlrev_b32_e32 v12, 5, v135
	v_and_b32_e32 v4, 0x7f, v4
	v_and_b32_e32 v8, 0x78, v8
	v_mov_b32_e32 v65, 0
	v_lshl_or_b32 v150, v4, 2, v6
	v_or_b32_e32 v20, v134, v12
	v_lshlrev_b32_e32 v6, 9, v136
	v_lshlrev_b32_e32 v8, 2, v8
	v_or_b32_e32 v21, v136, v12
	v_add_u32_e32 v14, 16, v133
	v_lshlrev_b32_e32 v64, 1, v1
	v_lshlrev_b32_e32 v4, 7, v20
	v_or3_b32 v151, v10, v6, v8
	v_lshlrev_b32_e32 v6, 7, v21
	v_and_b32_e32 v14, 0x78, v14
	v_add_u32_e32 v16, 24, v133
	v_lshlrev_b32_e32 v68, 12, v20
	v_lshlrev_b32_e32 v70, 12, v21
	v_lshl_add_u64 v[20:21], s[50:51], 0, v[64:65]
	s_mov_b64 s[0:1], 0xba00000
	v_lshlrev_b32_e32 v64, 9, v157
	v_lshlrev_b32_e32 v8, 9, v132
	v_lshlrev_b32_e32 v14, 2, v14
	v_and_b32_e32 v16, 0x78, v16
	v_or_b32_e32 v18, 16, v12
	v_lshl_add_u64 v[84:85], v[20:21], 0, s[0:1]
	v_lshl_add_u64 v[20:21], s[50:51], 0, v[64:65]
	v_lshlrev_b32_e32 v64, 1, v2
	v_or3_b32 v160, v10, v8, v14
	v_or_b32_e32 v26, v132, v12
	v_lshlrev_b32_e32 v14, 9, v130
	v_lshlrev_b32_e32 v16, 2, v16
	v_or_b32_e32 v27, v130, v12
	v_or_b32_e32 v28, v18, v134
	v_or_b32_e32 v29, v136, v18
	v_or_b32_e32 v30, v132, v18
	v_or_b32_e32 v31, v130, v18
	v_lshl_add_u64 v[20:21], v[20:21], 0, v[64:65]
	s_mov_b64 s[0:1], 0x1000000
	v_and_b32_e32 v0, 0x7f000, v156
	v_and_b32_e32 v3, 14, v153
	v_lshlrev_b32_e32 v5, 7, v138
	v_lshlrev_b32_e32 v11, 4, v152
	v_lshlrev_b32_e32 v8, 7, v26
	v_or3_b32 v161, v10, v14, v16
	v_lshlrev_b32_e32 v10, 7, v27
	v_lshlrev_b32_e32 v12, 7, v28
	v_lshlrev_b32_e32 v14, 7, v29
	v_lshlrev_b32_e32 v16, 7, v30
	v_lshlrev_b32_e32 v18, 7, v31
	s_add_u32 s33, s50, 0x3a00000
	v_lshl_add_u64 v[86:87], v[20:21], 0, s[0:1]
	v_lshl_add_u64 v[20:21], s[50:51], 0, v[64:65]
	s_mov_b64 s[0:1], 0x1a00000
	v_lshlrev_b32_e32 v66, 3, v138
	v_and_b32_e32 v162, 0x70, v129
	v_mov_b32_e32 v69, v65
	v_mov_b32_e32 v71, v65
	v_lshlrev_b32_e32 v72, 12, v26
	v_mov_b32_e32 v73, v65
	v_lshlrev_b32_e32 v74, 12, v27
	v_mov_b32_e32 v75, v65
	v_lshlrev_b32_e32 v76, 12, v28
	v_mov_b32_e32 v77, v65
	v_lshlrev_b32_e32 v78, 12, v29
	v_mov_b32_e32 v79, v65
	v_lshlrev_b32_e32 v80, 12, v30
	v_mov_b32_e32 v81, v65
	v_lshlrev_b32_e32 v82, 12, v31
	v_mov_b32_e32 v83, v65
	s_addc_u32 s44, s51, 0
	v_lshl_add_u64 v[88:89], v[20:21], 0, s[0:1]
	s_mov_b32 s45, 0xc2fc0000
	s_mov_b32 s46, 0x3f2aaaab
	v_mov_b32_e32 v163, 0x3ecc95a3
	s_mov_b32 s47, 0x3f317218
	s_mov_b32 s52, 0x33800000
	s_mov_b32 s19, 0
	v_lshlrev_b32_e32 v90, 1, v0
	v_lshlrev_b32_e32 v92, 1, v2
	s_mov_b64 s[20:21], 0x40000
	v_add_u32_e32 v164, 0x1000, v129
	s_mov_b64 s[22:23], 0x80000
	v_add_u32_e32 v165, 0x2000, v129
	s_mov_b64 s[24:25], 0xc0000
	v_add_u32_e32 v166, 0x3000, v129
	s_movk_i32 s53, 0x7fff
	v_add_u32_e32 v167, v13, v3
	v_add_u32_e32 v168, v15, v3
	v_add_u32_e32 v169, v17, v3
	v_add_u32_e32 v170, v19, v3
	v_add_u32_e32 v171, v22, v3
	v_add_u32_e32 v172, v23, v3
	v_add_u32_e32 v173, v24, v3
	v_add_u32_e32 v174, v25, v3
	v_add_u32_e32 v175, v7, v9
	v_add_u32_e32 v176, v7, v5
	v_add_u32_e32 v177, v11, v9
	v_add_u32_e32 v178, v11, v5
	s_mov_b32 s54, 0x7060302
	v_lshlrev_b32_e32 v94, 1, v4
	v_lshlrev_b32_e32 v96, 1, v6
	v_lshlrev_b32_e32 v98, 1, v8
	v_lshlrev_b32_e32 v100, 1, v10
	v_lshlrev_b32_e32 v102, 1, v12
	v_lshlrev_b32_e32 v104, 1, v14
	v_lshlrev_b32_e32 v106, 1, v16
	v_lshlrev_b32_e32 v108, 1, v18
	s_mov_b64 s[26:27], 0x4000
	s_mov_b64 s[28:29], 0x8000
	s_mov_b64 s[30:31], 0xc000
	s_mov_b64 s[34:35], 0x10000
	s_movk_i32 s55, 0xf800
	v_mov_b32_e32 v179, 0x42800000
	v_mov_b32_e32 v180, 0x7fc00000
	v_mov_b32_e32 v181, 0xff800000
	s_mov_b32 s56, s2
	s_mov_b32 s99, 0
	s_cmp_eq_u32 s3, 0x200
	s_cbranch_scc0 .Lmy_m1a_gen
	s_and_b32 s70, s2, 0x100
	s_lshr_b32 s73, s70, 7
	s_xor_b32 s73, s73, s2
	s_add_i32 s65, s73, 0x200
	s_add_i32 s66, s2, 0x400
	s_add_i32 s67, s2, 0x600
	s_xor_b32 s68, s2, 2
	s_add_i32 s68, s68, 0x600
	s_lshr_b32 s69, s73, 1
	s_lshr_b32 s71, s73, 2
	s_xor_b32 s69, s69, s71
	s_and_b32 s69, s69, 1
	s_cmp_lg_u32 s69, 0
	s_cselect_b32 s71, s67, -1
	s_cselect_b32 s72, s68, -1
	s_mov_b32 s60, s73
	s_mov_b32 s61, s65
	s_mov_b32 s62, s66
	s_mov_b32 s63, s71
	s_mov_b32 s64, s72
	s_cmp_eq_u32 s70, 0
	s_cbranch_scc1 .Lmy_m1a_go
	s_mov_b32 s60, s66
	s_cmp_lg_u32 s69, 0
	s_cselect_b32 s61, s67, s73
	s_cselect_b32 s62, s68, s65
	s_cselect_b32 s63, s73, -1
	s_cselect_b32 s64, s65, -1
